# grid barrier: acquire-side buffer_inv issued at arrival, overlapped with the arrival atomic round trip, instead of after release (one workgroup per CU, all waves parked in between)
# speedup vs baseline: 1.0144x; 1.0036x over previous
; __device__ __forceinline__ unsigned xb_add(unsigned* p, unsigned v) { return __hip_atomic_fetch_add(p, v, __ATOMIC_RELAXED, __HIP_MEMORY_SCOPE_AGENT); }
; __device__ __forceinline__ void xcd_barrier(const XcdBarrier& b) {
;     ...
;         __builtin_amdgcn_s_waitcnt(0);
;         unsigned nloc = b.st[0], nx = b.st[1];
;         if (nloc == 0u) { xcd_barrier_complete(bar, b.x, nloc, nx); b.st[0] = nloc; b.st[1] = nx; }
;         const unsigned old = xb_add(&bar[XB_XSUB(b.x)], 1u);
;         const unsigned gen = old / nloc;
;     ...
;             __builtin_amdgcn_fence(__ATOMIC_ACQUIRE, "agent");
;             asm volatile("s_waitcnt vmcnt(0)" ::: "memory");
.LBB0_153:
	s_mov_b64 s[2:3], exec
	v_mbcnt_lo_u32_b32 v1, s2, 0
	v_mbcnt_hi_u32_b32 v1, s3, v1
	v_cmp_eq_u32_e32 vcc, 0, v1
	s_and_saveexec_b64 s[0:1], vcc
	s_cbranch_execz .LBB0_155
	s_bcnt1_i32_b64 s2, s[2:3]
	v_mov_b32_e32 v3, s2
	v_readlane_b32 s2, v252, 3
	v_readlane_b32 s3, v252, 4
	s_nop 4
	buffer_inv sc1
	global_atomic_add v3, v17, v3, s[2:3] sc0

; __device__ __forceinline__ unsigned xb_ld(unsigned* p)              { return __hip_atomic_load(p, __ATOMIC_RELAXED, __HIP_MEMORY_SCOPE_AGENT); }
; #define XB_SPIN(cond, bar) do { unsigned _sp = 0; while (cond) { __builtin_amdgcn_s_sleep(0); \
;     if ((++_sp & 255u) == 0u) { if (xb_ld(&(bar)[XB_TMO])) break; if (_sp > XB_SPIN_CAP) { atomicAdd(&(bar)[XB_TMO], 1u); break; } } } } while (0)
; __device__ __forceinline__ void xcd_barrier(const XcdBarrier& b) {
;     ...
;             XB_SPIN(xb_ld(&bar[XB_XGEN(b.x)]) == gen, bar);
;             __builtin_amdgcn_fence(__ATOMIC_ACQUIRE, "agent");
;             asm volatile("s_waitcnt vmcnt(0)" ::: "memory");
.LBB0_168:
	s_or_b64 exec, exec, s[2:3]
	s_waitcnt vmcnt(0)
	s_waitcnt vmcnt(0)

; __device__ __forceinline__ unsigned xb_ld(unsigned* p)              { return __hip_atomic_load(p, __ATOMIC_RELAXED, __HIP_MEMORY_SCOPE_AGENT); }
; __device__ __forceinline__ unsigned xb_add(unsigned* p, unsigned v) { return __hip_atomic_fetch_add(p, v, __ATOMIC_RELAXED, __HIP_MEMORY_SCOPE_AGENT); }
; #define XB_SPIN(cond, bar) do { unsigned _sp = 0; while (cond) { __builtin_amdgcn_s_sleep(0); \
;     if ((++_sp & 255u) == 0u) { if (xb_ld(&(bar)[XB_TMO])) break; if (_sp > XB_SPIN_CAP) { atomicAdd(&(bar)[XB_TMO], 1u); break; } } } } while (0)
; __device__ __forceinline__ void xcd_barrier(const XcdBarrier& b) {
;     ...
;             const unsigned og = xb_add(&bar[XB_TOP], 1u);
;             const unsigned tg = og / nx;
;             if (og + 1u == (tg + 1u) * nx) xb_add(&bar[XB_TOPGEN], 1u);
;             else XB_SPIN(xb_ld(&bar[XB_TOPGEN]) == tg, bar);
;             __builtin_amdgcn_fence(__ATOMIC_ACQUIRE, "agent");
;             xb_add(&bar[XB_XGEN(b.x)], 1u);
;             asm volatile("s_waitcnt vmcnt(0)" ::: "memory");
.LBB0_186:
	s_or_b64 exec, exec, s[0:1]
	s_mov_b64 s[0:1], exec
	v_mbcnt_lo_u32_b32 v0, s0, 0
	v_mbcnt_hi_u32_b32 v0, s1, v0
	v_cmp_eq_u32_e32 vcc, 0, v0
	s_waitcnt vmcnt(0)
	s_and_saveexec_b64 s[2:3], vcc
	s_cbranch_execz .LBB0_188
	s_bcnt1_i32_b64 s0, s[0:1]
	v_mov_b32_e32 v0, s0
	v_readlane_b32 s0, v252, 5
	v_readlane_b32 s1, v252, 6
	s_nop 4
	global_atomic_add v17, v0, s[0:1]
